# c22 + attention: next-item queue atomic issued at item start (fully hidden behind the item)
# speedup vs baseline: 1.0019x; 1.0019x over previous
.LBB0_831:
	s_or_b64 exec, exec, s[0:1]
	s_movk_i32 s0, 0x48
	v_mul_lo_u32 v9, v4, s0
	s_waitcnt vmcnt(2)
	v_cvt_pk_bf16_f32 v10, v84, v85
	v_cvt_pk_bf16_f32 v11, v86, v87
	v_cvt_pk_bf16_f32 v12, v80, v81
	v_cvt_pk_bf16_f32 v13, v82, v83
	v_add_lshl_u32 v110, v9, v6, 1
	ds_write_b128 v110, v[10:13]
	s_waitcnt vmcnt(0)
	v_cvt_pk_bf16_f32 v10, v92, v93
	v_cvt_pk_bf16_f32 v11, v94, v95
	v_cvt_pk_bf16_f32 v12, v88, v89
	v_cvt_pk_bf16_f32 v13, v90, v91
	v_lshlrev_b32_e32 v111, 2, v3
	ds_write_b128 v110, v[10:13] offset:9216
	s_and_saveexec_b64 s[0:1], s[4:5]
	ds_write_b32 v111, v109 offset:18432
	s_or_b64 exec, exec, s[0:1]
	s_waitcnt lgkmcnt(2)
	v_add_f32_e32 v3, v7, v8
	v_mul_f32_e32 v3, v5, v3
	s_mov_b32 s0, 0xf800000
	v_mul_f32_e32 v5, 0x4f800000, v3
	v_cmp_gt_f32_e32 vcc, s0, v3
	v_lshlrev_b32_e32 v100, 2, v2
	s_add_i32 s70, s8, s63
	v_cndmask_b32_e32 v3, v3, v5, vcc
	v_sqrt_f32_e32 v5, v3
	s_cmp_lt_u32 s63, s69
	s_movk_i32 s0, 0x90
	v_mov_b32_e32 v14, v97
	v_add_u32_e32 v6, -1, v5
	v_fma_f32 v7, -v6, v5, v3
	v_cmp_ge_f32_e64 s[6:7], 0, v7
	v_add_u32_e32 v7, 1, v5
	v_mov_b32_e32 v15, v97
	v_cndmask_b32_e64 v6, v5, v6, s[6:7]
	v_fma_f32 v5, -v7, v5, v3
	v_cmp_lt_f32_e64 s[6:7], 0, v5
	v_add_u32_e32 v113, s8, v101
	s_cselect_b64 s[34:35], -1, 0
	v_cndmask_b32_e64 v5, v6, v7, s[6:7]
	v_mul_f32_e32 v6, 0x37800000, v5
	v_cndmask_b32_e32 v5, v5, v6, vcc
	v_cmp_class_f32_e32 vcc, v3, v103
	v_and_b32_e32 v114, 16, v0
	v_cmp_eq_u32_e64 s[8:9], 0, v0
	v_cndmask_b32_e32 v3, v5, v3, vcc
	v_fmamk_f32 v112, v3, 0x3f8147ae, v99
	v_lshrrev_b32_e32 v3, 2, v0
	v_and_or_b32 v2, v3, 3, v100
	v_lshlrev_b32_e32 v3, 2, v0
	v_and_b32_e32 v16, 12, v3
	v_mul_u32_u24_e32 v115, 0x48, v1
	v_mul_lo_u32 v116, v2, s0
	v_add_u32_e32 v117, s64, v0
	v_subrev_u32_e32 v118, 64, v4
	s_lshr_b32 s0, s44, 3
	v_mov_b32_e32 v0, v97
	v_mov_b32_e32 v1, v97
	v_mov_b32_e32 v2, v97
	v_mov_b32_e32 v3, v97
	v_mov_b32_e32 v4, v97
	v_mov_b32_e32 v5, v97
	v_mov_b32_e32 v6, v97
	v_mov_b32_e32 v7, v97
	v_mov_b32_e32 v8, v97
	v_mov_b32_e32 v9, v97
	v_mov_b32_e32 v10, v97
	v_mov_b32_e32 v11, v97
	v_mov_b32_e32 v12, v97
	v_mov_b32_e32 v13, v97
	v_lshlrev_b32_e32 v120, 1, v16
	v_mov_b64_e32 v[30:31], v[14:15]
	s_mov_b32 s31, 0
	s_add_i32 s71, s70, 31
	v_cmp_le_u32_e64 s[6:7], s69, v101
	s_and_b32 s72, s0, 0x1ffffff8
	v_mov_b32_e32 v119, 0
	v_mov_b32_e32 v122, 0xf149f2ca
	v_mov_b64_e32 v[28:29], v[12:13]
	v_mov_b64_e32 v[26:27], v[10:11]
	v_mov_b64_e32 v[24:25], v[8:9]
	v_mov_b64_e32 v[22:23], v[6:7]
	v_mov_b64_e32 v[20:21], v[4:5]
	v_mov_b64_e32 v[18:19], v[2:3]
	v_mov_b64_e32 v[16:17], v[0:1]
	s_waitcnt lgkmcnt(0)
	s_barrier
	s_and_b64 vcc, exec, s[2:3]
	s_cbranch_vccnz .Laq_skip
	v_mbcnt_lo_u32_b32 v152, -1, 0
	v_mbcnt_hi_u32_b32 v152, -1, v152
	v_cmp_eq_u32_e32 vcc, 0, v152
	s_and_saveexec_b64 s[92:93], vcc
	v_mov_b32_e32 v153, 1
	global_atomic_add v153, v97, v153, s[12:13] offset:64 sc0
	s_or_b64 exec, exec, s[92:93]
.Laq_skip:
	s_branch .LBB0_835
.LBB0_834:
	s_or_b64 exec, exec, s[0:1]
	v_mov_b32_e32 v36, s44
	s_waitcnt lgkmcnt(0)
	s_barrier
	ds_read_b128 v[32:35], v36
	ds_read_b128 v[36:39], v36 offset:16
	s_cmp_lg_u32 s72, 0
	s_cselect_b64 s[0:1], -1, 0
	s_sub_i32 s10, s10, 64
	s_waitcnt lgkmcnt(1)
	v_or_b32_e32 v32, v32, v33
	v_or_b32_e32 v32, v32, v34
	v_or_b32_e32 v32, v32, v35
	s_waitcnt lgkmcnt(0)
	v_or_b32_e32 v32, v32, v37
	v_or_b32_e32 v32, v32, v36
	v_or_b32_e32 v32, v32, v38
	v_or_b32_e32 v32, v32, v39
	v_cmp_ne_u32_e32 vcc, 0, v32
	s_and_b64 s[0:1], s[0:1], vcc
	s_add_i32 s72, s72, -8
	s_and_b64 vcc, exec, s[0:1]
	s_cbranch_vccz .LBB0_853

.LBB0_853:
	s_mov_b32 s94, 1
	ds_bpermute_b32 v32, v108, v119
	v_cmp_gt_u32_e32 vcc, s69, v101
	s_and_saveexec_b64 s[0:1], vcc
	s_xor_b64 s[4:5], exec, s[0:1]
	s_cbranch_execz .LBB0_807
	s_waitcnt lgkmcnt(0)
	v_add_f32_e32 v32, v119, v32
	v_div_scale_f32 v33, s[0:1], v32, v32, 1.0
	v_rcp_f32_e32 v34, v33
	v_div_scale_f32 v35, vcc, 1.0, v32, 1.0
	s_mov_b32 s31, s11
	v_fma_f32 v36, -v33, v34, 1.0
	v_fmac_f32_e32 v34, v36, v34
	v_mul_f32_e32 v36, v35, v34
	v_fma_f32 v37, -v33, v36, v35
	v_fmac_f32_e32 v36, v37, v34
	v_fma_f32 v33, -v33, v36, v35
	v_div_fmas_f32 v33, v33, v34, v36
	v_add_u32_e32 v34, s68, v101
	v_ashrrev_i32_e32 v35, 31, v34
	v_lshlrev_b64 v[34:35], 11, v[34:35]
	v_div_fixup_f32 v32, v33, v32, 1.0
	v_lshl_add_u64 v[34:35], s[16:17], 0, v[34:35]
	v_lshl_add_u64 v[34:35], v[34:35], 0, s[30:31]
	v_ashrrev_i32_e32 v101, 31, v100
	v_pk_mul_f32 v[16:17], v[16:17], v[32:33] op_sel_hi:[1,0]
	v_pk_mul_f32 v[18:19], v[18:19], v[32:33] op_sel_hi:[1,0]
	v_pk_mul_f32 v[0:1], v[0:1], v[32:33] op_sel_hi:[1,0]
	v_pk_mul_f32 v[2:3], v[2:3], v[32:33] op_sel_hi:[1,0]
	v_lshl_add_u64 v[34:35], v[100:101], 1, v[34:35]
	v_cvt_pk_bf16_f32 v16, v16, v17
	v_cvt_pk_bf16_f32 v17, v18, v19
	v_cvt_pk_bf16_f32 v0, v0, v1
	v_cvt_pk_bf16_f32 v1, v2, v3
	global_store_dwordx2 v[34:35], v[16:17], off
	v_pk_mul_f32 v[16:17], v[20:21], v[32:33] op_sel_hi:[1,0]
	v_pk_mul_f32 v[18:19], v[22:23], v[32:33] op_sel_hi:[1,0]
	global_store_dwordx2 v[34:35], v[0:1], off offset:64
	v_pk_mul_f32 v[0:1], v[4:5], v[32:33] op_sel_hi:[1,0]
	v_pk_mul_f32 v[2:3], v[6:7], v[32:33] op_sel_hi:[1,0]
	v_cvt_pk_bf16_f32 v16, v16, v17
	v_cvt_pk_bf16_f32 v17, v18, v19
	v_cvt_pk_bf16_f32 v0, v0, v1
	v_cvt_pk_bf16_f32 v1, v2, v3
	global_store_dwordx2 v[34:35], v[16:17], off offset:16
	v_pk_mul_f32 v[16:17], v[24:25], v[32:33] op_sel_hi:[1,0]
	v_pk_mul_f32 v[18:19], v[26:27], v[32:33] op_sel_hi:[1,0]
	global_store_dwordx2 v[34:35], v[0:1], off offset:80
	v_pk_mul_f32 v[0:1], v[8:9], v[32:33] op_sel_hi:[1,0]
	v_pk_mul_f32 v[2:3], v[10:11], v[32:33] op_sel_hi:[1,0]
	v_cvt_pk_bf16_f32 v16, v16, v17
	v_cvt_pk_bf16_f32 v17, v18, v19
	v_cvt_pk_bf16_f32 v0, v0, v1
	v_cvt_pk_bf16_f32 v1, v2, v3
	global_store_dwordx2 v[34:35], v[16:17], off offset:32
	v_pk_mul_f32 v[16:17], v[28:29], v[32:33] op_sel_hi:[1,0]
	v_pk_mul_f32 v[18:19], v[30:31], v[32:33] op_sel_hi:[1,0]
	global_store_dwordx2 v[34:35], v[0:1], off offset:96
	v_pk_mul_f32 v[0:1], v[12:13], v[32:33] op_sel_hi:[1,0]
	v_pk_mul_f32 v[2:3], v[14:15], v[32:33] op_sel_hi:[1,0]
	v_cvt_pk_bf16_f32 v16, v16, v17
	v_cvt_pk_bf16_f32 v17, v18, v19
	v_cvt_pk_bf16_f32 v0, v0, v1
	v_cvt_pk_bf16_f32 v1, v2, v3
	global_store_dwordx2 v[34:35], v[16:17], off offset:48
	global_store_dwordx2 v[34:35], v[0:1], off offset:112
	s_branch .LBB0_807
